# static s_setprio 1 for the trailing wave group in the in-proj, out-proj, MLP1 and MLP2 GEMM loops (reset at the epilogues)
# baseline (speedup 1.0000x reference)
; DEVI void gemm16s(f32x4 (&acc)[4][8], const GUnit& cur, const GUnit& nxt, bool has_next, bool first, int& stg, bfu* lds) {
;     ...
; #pragma unroll 1
;     for (int kt = 0; kt < nkt; ++kt) {
;       G16_HEAD()
;       ISSUE16(Ai, Bi, sAi, sBi, vAi, vBi, tk, st ^ 1);
;       G16_MM(ctf, cwf)
;       bf16x8 tf0[8], wf0[4];
;       G16_RD(tf0, wf0, 0)
;       G16_MM(tf0, wf0)
;       bf16x8 tf1[8], wf1[4];
;       G16_RD(tf1, wf1, 1)
; #pragma unroll
;       for (int mi = 0; mi < 8; ++mi) ctf[mi] = tf1[mi];
; #pragma unroll
;       for (int ni = 0; ni < 4; ++ni) cwf[ni] = wf1[ni];
; #pragma unroll
;       for (int i = 0; i < 8; ++i) {
;         __builtin_amdgcn_sched_group_barrier(0x008, 4, 0);
;         __builtin_amdgcn_sched_group_barrier(0x020, 1, 0);
;       }
;       __builtin_amdgcn_sched_group_barrier(0x100, 12, 0);
; #pragma unroll
;       for (int i = 0; i < 12; ++i) {
;         __builtin_amdgcn_sched_group_barrier(0x008, 2, 0);
;         __builtin_amdgcn_sched_group_barrier(0x100, 1, 0);
;       }
;       __builtin_amdgcn_sched_group_barrier(0x008, 8, 0);
;       st ^= 1;
;     }
.LBB0_29:
	s_setprio 1
	s_add_i32 s23, s30, 1
	s_cmp_gt_u32 s30, 62
	s_cselect_b64 s[36:37], -1, 0
	s_and_b64 s[60:61], s[36:37], exec
	s_cselect_b32 s30, s59, s23
	s_and_b64 s[36:37], s[40:41], s[36:37]
	s_and_b64 s[36:37], s[36:37], exec
	s_cselect_b32 s37, s49, s45
	s_cselect_b32 s62, s29, s44
	s_cselect_b32 s64, s58, s51
	s_cselect_b32 s65, s57, s50
	s_lshl_b32 s36, s20, 16
	s_xor_b32 s20, s20, 1
	s_lshl_b32 s60, s20, 16
	s_addk_i32 s36, 0xc20
	s_add_i32 s66, s28, s60
	s_lshl_b64 s[60:61], s[30:31], 7
	s_add_u32 s62, s62, s60
	s_addc_u32 s63, s37, s61
	s_waitcnt vmcnt(0)
	v_lshl_add_u64 v[190:191], s[62:63], 0, v[0:1]
	s_mov_b32 m0, s66
	s_waitcnt lgkmcnt(0)
	s_barrier
	v_lshl_add_u64 v[192:193], v[190:191], 0, s[68:69]
	s_waitcnt lgkmcnt(0)
	v_mfma_f32_16x16x32_bf16 v[162:165], v[134:137], v[126:129], v[162:165]
	s_mov_b32 s30, s23
	v_mfma_f32_16x16x32_bf16 v[118:121], v[134:137], v[130:133], v[118:121]
	v_mfma_f32_16x16x32_bf16 v[98:101], v[134:137], v[138:141], v[98:101]
	v_mfma_f32_16x16x32_bf16 v[82:85], v[134:137], v[142:145], v[82:85]
	global_load_lds_dwordx4 v[190:191], off
	s_add_i32 m0, s66, 0x2000
	v_mfma_f32_16x16x32_bf16 v[66:69], v[134:137], v[150:153], v[66:69]
	v_mfma_f32_16x16x32_bf16 v[50:53], v[134:137], v[154:157], v[50:53]
	v_mfma_f32_16x16x32_bf16 v[34:37], v[134:137], v[158:161], v[34:37]
	v_mfma_f32_16x16x32_bf16 v[14:17], v[134:137], v[146:149], v[14:17]
	global_load_lds_dwordx4 v[192:193], off
	v_lshl_add_u64 v[192:193], v[190:191], 0, s[70:71]
	s_add_i32 m0, s66, 0x4000
	v_mfma_f32_16x16x32_bf16 v[122:125], v[174:177], v[126:129], v[122:125]
	v_lshl_add_u64 v[190:191], v[190:191], 0, s[74:75]
	v_mfma_f32_16x16x32_bf16 v[106:109], v[174:177], v[130:133], v[106:109]
	v_mfma_f32_16x16x32_bf16 v[90:93], v[174:177], v[138:141], v[90:93]
	v_mfma_f32_16x16x32_bf16 v[74:77], v[174:177], v[142:145], v[74:77]
	global_load_lds_dwordx4 v[192:193], off
	s_add_i32 m0, s66, 0x6000
	s_add_u32 s60, s65, s60
	s_addc_u32 s61, s64, s61
	v_mfma_f32_16x16x32_bf16 v[58:61], v[174:177], v[150:153], v[58:61]
	v_mfma_f32_16x16x32_bf16 v[42:45], v[174:177], v[154:157], v[42:45]
	v_mfma_f32_16x16x32_bf16 v[26:29], v[174:177], v[158:161], v[26:29]
	v_mfma_f32_16x16x32_bf16 v[10:13], v[174:177], v[146:149], v[10:13]
	global_load_lds_dwordx4 v[190:191], off
	v_lshl_add_u64 v[190:191], s[60:61], 0, v[0:1]
	s_add_i32 m0, s66, 0x8000
	v_lshl_add_u64 v[192:193], v[190:191], 0, s[68:69]
	v_mfma_f32_16x16x32_bf16 v[114:117], v[170:173], v[126:129], v[114:117]
	v_mfma_f32_16x16x32_bf16 v[102:105], v[170:173], v[130:133], v[102:105]
	v_mfma_f32_16x16x32_bf16 v[86:89], v[170:173], v[138:141], v[86:89]
	v_mfma_f32_16x16x32_bf16 v[70:73], v[170:173], v[142:145], v[70:73]
	global_load_lds_dwordx4 v[190:191], off
	s_add_i32 m0, s66, 0xa000
	v_mfma_f32_16x16x32_bf16 v[54:57], v[170:173], v[150:153], v[54:57]
	v_mfma_f32_16x16x32_bf16 v[38:41], v[170:173], v[154:157], v[38:41]
	v_mfma_f32_16x16x32_bf16 v[22:25], v[170:173], v[158:161], v[22:25]
	v_mfma_f32_16x16x32_bf16 v[6:9], v[170:173], v[146:149], v[6:9]
	global_load_lds_dwordx4 v[192:193], off
	v_lshl_add_u64 v[192:193], v[190:191], 0, s[70:71]
	s_add_i32 m0, s66, 0xc000
	v_lshl_add_u64 v[190:191], v[190:191], 0, s[74:75]
	v_mfma_f32_16x16x32_bf16 v[110:113], v[166:169], v[126:129], v[110:113]
	v_mfma_f32_16x16x32_bf16 v[94:97], v[166:169], v[130:133], v[94:97]
	v_mfma_f32_16x16x32_bf16 v[78:81], v[166:169], v[138:141], v[78:81]
	v_mfma_f32_16x16x32_bf16 v[62:65], v[166:169], v[142:145], v[62:65]
	global_load_lds_dwordx4 v[192:193], off
	s_add_i32 m0, s66, 0xe000
	v_mfma_f32_16x16x32_bf16 v[46:49], v[166:169], v[150:153], v[46:49]
	s_cmp_eq_u32 s23, 64
	v_mfma_f32_16x16x32_bf16 v[30:33], v[166:169], v[154:157], v[30:33]
	v_mfma_f32_16x16x32_bf16 v[18:21], v[166:169], v[158:161], v[18:21]
	v_add_u32_e32 v158, s36, v185
	v_add3_u32 v174, v158, v189, v188
	v_add3_u32 v154, v158, v187, v188
	v_mfma_f32_16x16x32_bf16 v[2:5], v[166:169], v[146:149], v[2:5]
	global_load_lds_dwordx4 v[190:191], off
	ds_read_b128 v[158:161], v174 offset:32768
	ds_read_b128 v[166:169], v174 offset:34816
	ds_read_b128 v[170:173], v174 offset:36864
	ds_read_b128 v[174:177], v174 offset:38912
	ds_read_b128 v[126:129], v154
	ds_read_b128 v[130:133], v154 offset:2048
	ds_read_b128 v[134:137], v154 offset:4096
	ds_read_b128 v[138:141], v154 offset:6144
	ds_read_b128 v[142:145], v154 offset:8192
	ds_read_b128 v[146:149], v154 offset:10240
	ds_read_b128 v[150:153], v154 offset:12288
	ds_read_b128 v[154:157], v154 offset:14336
	s_waitcnt lgkmcnt(0)
; DEVI void gemm16s(f32x4 (&acc)[4][8], const GUnit& cur, const GUnit& nxt, bool has_next, bool first, int& stg, bfu* lds) {
;     ...
; #pragma unroll 1
;     for (int kt = 0; kt < nkt; ++kt) {
;       G16_HEAD()
;       ISSUE16(Ai, Bi, sAi, sBi, vAi, vBi, tk, st ^ 1);
;       G16_MM(ctf, cwf)
;       bf16x8 tf0[8], wf0[4];
;       G16_RD(tf0, wf0, 0)
;       G16_MM(tf0, wf0)
;       bf16x8 tf1[8], wf1[4];
;       G16_RD(tf1, wf1, 1)
; #pragma unroll
;       for (int mi = 0; mi < 8; ++mi) ctf[mi] = tf1[mi];
; #pragma unroll
;       for (int ni = 0; ni < 4; ++ni) cwf[ni] = wf1[ni];
; #pragma unroll
;       for (int i = 0; i < 8; ++i) {
;         __builtin_amdgcn_sched_group_barrier(0x008, 4, 0);
;         __builtin_amdgcn_sched_group_barrier(0x020, 1, 0);
;       }
;       __builtin_amdgcn_sched_group_barrier(0x100, 12, 0);
; #pragma unroll
;       for (int i = 0; i < 12; ++i) {
;         __builtin_amdgcn_sched_group_barrier(0x008, 2, 0);
;         __builtin_amdgcn_sched_group_barrier(0x100, 1, 0);
;       }
;       __builtin_amdgcn_sched_group_barrier(0x008, 8, 0);
;       st ^= 1;
;     }
;     G16_MM(ctf, cwf)
	v_mfma_f32_16x16x32_bf16 v[162:165], v[158:161], v[126:129], v[162:165]
	v_mfma_f32_16x16x32_bf16 v[118:121], v[158:161], v[130:133], v[118:121]
	v_mfma_f32_16x16x32_bf16 v[98:101], v[158:161], v[134:137], v[98:101]
	v_mfma_f32_16x16x32_bf16 v[82:85], v[158:161], v[138:141], v[82:85]
	v_mfma_f32_16x16x32_bf16 v[122:125], v[166:169], v[126:129], v[122:125]
	v_mfma_f32_16x16x32_bf16 v[106:109], v[166:169], v[130:133], v[106:109]
	v_mfma_f32_16x16x32_bf16 v[90:93], v[166:169], v[134:137], v[90:93]
	v_mfma_f32_16x16x32_bf16 v[74:77], v[166:169], v[138:141], v[74:77]
	v_mfma_f32_16x16x32_bf16 v[58:61], v[166:169], v[142:145], v[58:61]
	v_mfma_f32_16x16x32_bf16 v[42:45], v[166:169], v[146:149], v[42:45]
	v_mfma_f32_16x16x32_bf16 v[26:29], v[166:169], v[150:153], v[26:29]
	v_mfma_f32_16x16x32_bf16 v[10:13], v[166:169], v[154:157], v[10:13]
	v_mfma_f32_16x16x32_bf16 v[114:117], v[170:173], v[126:129], v[114:117]
	v_mfma_f32_16x16x32_bf16 v[102:105], v[170:173], v[130:133], v[102:105]
	v_mfma_f32_16x16x32_bf16 v[86:89], v[170:173], v[134:137], v[86:89]
	v_mfma_f32_16x16x32_bf16 v[70:73], v[170:173], v[138:141], v[70:73]
	v_mfma_f32_16x16x32_bf16 v[54:57], v[170:173], v[142:145], v[54:57]
	v_mfma_f32_16x16x32_bf16 v[38:41], v[170:173], v[146:149], v[38:41]
	v_mfma_f32_16x16x32_bf16 v[22:25], v[170:173], v[150:153], v[22:25]
	v_mfma_f32_16x16x32_bf16 v[6:9], v[170:173], v[154:157], v[6:9]
	v_mfma_f32_16x16x32_bf16 v[78:81], v[174:177], v[134:137], v[78:81]
	v_add_u32_e32 v134, s36, v186
	v_add3_u32 v135, v134, v187, v188
	v_add3_u32 v166, v134, v189, v188
	ds_read_b128 v[170:173], v166 offset:36864
	v_mfma_f32_16x16x32_bf16 v[66:69], v[158:161], v[142:145], v[66:69]
	v_mfma_f32_16x16x32_bf16 v[50:53], v[158:161], v[146:149], v[50:53]
	v_mfma_f32_16x16x32_bf16 v[110:113], v[174:177], v[126:129], v[110:113]
	v_mfma_f32_16x16x32_bf16 v[94:97], v[174:177], v[130:133], v[94:97]
	v_mfma_f32_16x16x32_bf16 v[62:65], v[174:177], v[138:141], v[62:65]
	v_mfma_f32_16x16x32_bf16 v[46:49], v[174:177], v[142:145], v[46:49]
	v_mfma_f32_16x16x32_bf16 v[30:33], v[174:177], v[146:149], v[30:33]
	v_mfma_f32_16x16x32_bf16 v[18:21], v[174:177], v[150:153], v[18:21]
	v_mfma_f32_16x16x32_bf16 v[2:5], v[174:177], v[154:157], v[2:5]
	ds_read_b128 v[174:177], v166 offset:34816
	v_mfma_f32_16x16x32_bf16 v[34:37], v[158:161], v[150:153], v[34:37]
	v_mfma_f32_16x16x32_bf16 v[14:17], v[158:161], v[154:157], v[14:17]
	ds_read_b128 v[146:149], v135 offset:14336
	ds_read_b128 v[158:161], v135 offset:12288
	ds_read_b128 v[154:157], v135 offset:10240
	ds_read_b128 v[150:153], v135 offset:8192
	ds_read_b128 v[142:145], v135 offset:6144
	ds_read_b128 v[138:141], v135 offset:4096
	ds_read_b128 v[130:133], v135 offset:2048
	ds_read_b128 v[126:129], v135
	ds_read_b128 v[134:137], v166 offset:32768
	ds_read_b128 v[166:169], v166 offset:38912
	s_cbranch_scc0 .LBB0_29
	s_waitcnt lgkmcnt(0)
	v_mfma_f32_16x16x32_bf16 v[162:165], v[134:137], v[126:129], v[162:165]
	v_mfma_f32_16x16x32_bf16 v[118:121], v[134:137], v[130:133], v[118:121]
	v_mfma_f32_16x16x32_bf16 v[98:101], v[134:137], v[138:141], v[98:101]
	v_mfma_f32_16x16x32_bf16 v[82:85], v[134:137], v[142:145], v[82:85]
	v_mfma_f32_16x16x32_bf16 v[66:69], v[134:137], v[150:153], v[66:69]
	v_mfma_f32_16x16x32_bf16 v[50:53], v[134:137], v[154:157], v[50:53]
	v_mfma_f32_16x16x32_bf16 v[34:37], v[134:137], v[158:161], v[34:37]
	v_mfma_f32_16x16x32_bf16 v[14:17], v[134:137], v[146:149], v[14:17]
	v_mfma_f32_16x16x32_bf16 v[122:125], v[174:177], v[126:129], v[122:125]
	v_mfma_f32_16x16x32_bf16 v[106:109], v[174:177], v[130:133], v[106:109]
	v_mfma_f32_16x16x32_bf16 v[90:93], v[174:177], v[138:141], v[90:93]
	v_mfma_f32_16x16x32_bf16 v[74:77], v[174:177], v[142:145], v[74:77]
	v_mfma_f32_16x16x32_bf16 v[58:61], v[174:177], v[150:153], v[58:61]
	v_mfma_f32_16x16x32_bf16 v[42:45], v[174:177], v[154:157], v[42:45]
	v_mfma_f32_16x16x32_bf16 v[26:29], v[174:177], v[158:161], v[26:29]
	v_mfma_f32_16x16x32_bf16 v[10:13], v[174:177], v[146:149], v[10:13]
	v_mfma_f32_16x16x32_bf16 v[114:117], v[170:173], v[126:129], v[114:117]
	v_mfma_f32_16x16x32_bf16 v[102:105], v[170:173], v[130:133], v[102:105]
	v_mfma_f32_16x16x32_bf16 v[86:89], v[170:173], v[138:141], v[86:89]
	v_mfma_f32_16x16x32_bf16 v[70:73], v[170:173], v[142:145], v[70:73]
	v_mfma_f32_16x16x32_bf16 v[54:57], v[170:173], v[150:153], v[54:57]
	v_mfma_f32_16x16x32_bf16 v[38:41], v[170:173], v[154:157], v[38:41]
	v_mfma_f32_16x16x32_bf16 v[22:25], v[170:173], v[158:161], v[22:25]
	v_mfma_f32_16x16x32_bf16 v[6:9], v[170:173], v[146:149], v[6:9]
	v_mfma_f32_16x16x32_bf16 v[110:113], v[166:169], v[126:129], v[110:113]
	v_mfma_f32_16x16x32_bf16 v[94:97], v[166:169], v[130:133], v[94:97]
	v_mfma_f32_16x16x32_bf16 v[78:81], v[166:169], v[138:141], v[78:81]
	v_mfma_f32_16x16x32_bf16 v[62:65], v[166:169], v[142:145], v[62:65]
	v_mfma_f32_16x16x32_bf16 v[46:49], v[166:169], v[150:153], v[46:49]
	v_mfma_f32_16x16x32_bf16 v[30:33], v[166:169], v[154:157], v[30:33]
	v_mfma_f32_16x16x32_bf16 v[18:21], v[166:169], v[158:161], v[18:21]
	v_mfma_f32_16x16x32_bf16 v[2:5], v[166:169], v[146:149], v[2:5]
	s_branch .LBB0_36

; DEVI float lo2f(unsigned u) { return __uint_as_float(u << 16); }
; DEVI float hi2f(unsigned u) { return __uint_as_float(u & 0xffff0000u); }
; DEVI void phase_resid_gemm(const Params& p, const bfu* A, int lda, int nkt, const bfu* wT, int ldb, const float* resid32,
;                            float* ssq_out, float* out32, char* lds) {
;     ...
;     for (int mi = 0; mi < 8; ++mi) {
;       const int m = m0 + wm * 128 + mi * 16 + fr;
;       float ss = 0.f;
; #pragma unroll
;       for (int ni = 0; ni < 4; ++ni) {
;         const int n = n0 + wn * 64 + ni * 16 + fq * 4;
;         float4 r;
;         if (resid32) r = *(const float4*)(resid32 + (long)m * 1024 + n);
;         else { const uint2 u = *(const uint2*)(xs + (long)m * LDX + n); r = make_float4(lo2f(u.x), hi2f(u.x), lo2f(u.y), hi2f(u.y)); }
;         float4 o;
;         o.x = r.x + acc[ni][mi][0]; o.y = r.y + acc[ni][mi][1]; o.z = r.z + acc[ni][mi][2]; o.w = r.w + acc[ni][mi][3];
;         if (out32) *(float4*)(out32 + (long)m * 1024 + n) = o;
.LBB0_38:
	s_setprio 0
	s_lshl_b32 s20, s25, 8
	v_add_u32_e32 v132, s20, v179
	v_or_b32_e32 v130, s27, v181
	v_mov_b64_e32 v[126:127], s[2:3]
	v_mad_i64_i32 v[126:127], s[28:29], v132, s95, v[126:127]
	v_ashrrev_i32_e32 v131, 31, v130
	v_lshl_add_u64 v[134:135], v[130:131], 1, v[126:127]
	v_lshl_add_u64 v[218:219], v[134:135], 0, v[254:255]
	global_load_dwordx4 v[214:217], v[218:219], off
	v_ashrrev_i32_e32 v133, 31, v132
	v_lshlrev_b64 v[128:129], 12, v[132:133]
	v_cndmask_b32_e64 v0, 0, 1, s[46:47]
	v_lshl_add_u64 v[136:137], s[0:1], 0, v[128:129]
	s_mov_b64 s[36:37], -1
	v_cmp_ne_u32_e64 s[42:43], 1, v0
	s_andn2_b64 vcc, exec, s[46:47]
	v_lshl_add_u64 v[136:137], v[130:131], 2, v[136:137]
	s_waitcnt vmcnt(0)
	v_permlane16_swap_b32_e32 v214, v216
	v_permlane16_swap_b32_e32 v215, v217
	s_nop 1
	v_lshlrev_b32_e32 v128, 16, v214
	v_and_b32_e32 v129, 0xffff0000, v214
	v_lshlrev_b32_e32 v138, 16, v215
	v_and_b32_e32 v139, 0xffff0000, v215
	v_pk_add_f32 v[126:127], v[162:163], v[128:129]
	v_pk_add_f32 v[128:129], v[164:165], v[138:139]
	s_cbranch_vccnz .LBB0_40
	s_mov_b64 s[36:37], 0
	global_store_dwordx4 v[136:137], v[126:129], off nt

; DEVI void phase7(const Params& p, int l, char* lds) {
;     ...
;   for (int it = 0; have; ++it) {
;     int mt2 = 0, nt2 = 0;
;     const bool have2 = tile_map(it + 1, 16, mt2, nt2);
;     const int m0 = mt * 256, n0 = nt * 256;
;     const GUnit cur{hn + (long)m0 * LDX, wT + (long)n0 * LDX, LDX, LDX, 16};
;     const GUnit nxt{hn + (long)mt2 * 256 * LDX, wT + (long)nt2 * 256 * LDX, LDX, LDX, 16};
;     const float* rsS = stage_rstd((const float*)(p.ws + OFF_SSQB), m0, it, lds);
;     f32x4 acc[4][8];
;     zero_acc8(acc);
;     gemm16s(acc, cur, nxt, have2, it == 0, stg, (bfu*)lds);
;     mt = mt2; nt = nt2; have = have2;
.LBB0_204:
	s_setprio 0
	s_cmp_eq_u32 s100, 0
	s_cbranch_scc1 .Lp7_released
	v_readlane_b32 vcc_lo, v242, 28
	v_readlane_b32 vcc_hi, v242, 29

; DEVI void gemm16s(f32x4 (&acc)[4][8], const GUnit& cur, const GUnit& nxt, bool has_next, bool first, int& stg, bfu* lds) {
;     ...
; #pragma unroll 1
;     for (int kt = 0; kt < nkt; ++kt) {
;       G16_HEAD()
;       ISSUE16(Ai, Bi, sAi, sBi, vAi, vBi, tk, st ^ 1);
;       G16_MM(ctf, cwf)
;       bf16x8 tf0[8], wf0[4];
;       G16_RD(tf0, wf0, 0)
;       G16_MM(tf0, wf0)
;       bf16x8 tf1[8], wf1[4];
;       G16_RD(tf1, wf1, 1)
; #pragma unroll
;       for (int mi = 0; mi < 8; ++mi) ctf[mi] = tf1[mi];
; #pragma unroll
;       for (int ni = 0; ni < 4; ++ni) cwf[ni] = wf1[ni];
; #pragma unroll
;       for (int i = 0; i < 8; ++i) {
;         __builtin_amdgcn_sched_group_barrier(0x008, 4, 0);
;         __builtin_amdgcn_sched_group_barrier(0x020, 1, 0);
;       }
;       __builtin_amdgcn_sched_group_barrier(0x100, 12, 0);
; #pragma unroll
;       for (int i = 0; i < 12; ++i) {
;         __builtin_amdgcn_sched_group_barrier(0x008, 2, 0);
;         __builtin_amdgcn_sched_group_barrier(0x100, 1, 0);
;       }
;       __builtin_amdgcn_sched_group_barrier(0x008, 8, 0);
;       st ^= 1;
;     }
.LBB0_214:
	s_setprio 1
	s_add_i32 s23, s30, 1
	s_cmp_gt_u32 s30, 14
	s_cselect_b64 s[36:37], -1, 0
	s_and_b64 s[52:53], s[36:37], exec
	s_cselect_b32 s30, s51, s23
	s_and_b64 s[36:37], s[4:5], s[36:37]
	s_and_b64 s[36:37], s[36:37], exec
	s_cselect_b32 s37, s48, s39
	s_cselect_b32 s54, s47, s38
	s_cselect_b32 s56, s50, s41
	s_cselect_b32 s57, s49, s40
	s_lshl_b32 s36, s20, 16
	s_xor_b32 s20, s20, 1
	s_lshl_b32 s52, s20, 16
	s_addk_i32 s36, 0xc20
	s_add_i32 s58, s46, s52
	s_lshl_b64 s[52:53], s[30:31], 7
	s_add_u32 s54, s54, s52
	s_addc_u32 s55, s37, s53
	s_waitcnt vmcnt(0)
	v_lshl_add_u64 v[190:191], s[54:55], 0, v[0:1]
	s_mov_b32 m0, s58
	s_waitcnt lgkmcnt(0)
	s_barrier
	v_lshl_add_u64 v[192:193], v[190:191], 0, s[14:15]
	s_waitcnt lgkmcnt(0)
	v_mfma_f32_16x16x32_bf16 v[162:165], v[122:125], v[114:117], v[162:165]
	s_mov_b32 s30, s23
	v_mfma_f32_16x16x32_bf16 v[158:161], v[122:125], v[118:121], v[158:161]
	v_mfma_f32_16x16x32_bf16 v[150:153], v[122:125], v[126:129], v[150:153]
	v_mfma_f32_16x16x32_bf16 v[130:133], v[122:125], v[134:137], v[130:133]
	global_load_lds_dwordx4 v[190:191], off
	s_add_i32 m0, s58, 0x2000
	v_mfma_f32_16x16x32_bf16 v[110:113], v[122:125], v[142:145], v[110:113]
	v_mfma_f32_16x16x32_bf16 v[106:109], v[122:125], v[146:149], v[106:109]
	v_mfma_f32_16x16x32_bf16 v[102:105], v[122:125], v[154:157], v[102:105]
	v_mfma_f32_16x16x32_bf16 v[98:101], v[122:125], v[138:141], v[98:101]
	global_load_lds_dwordx4 v[192:193], off
	v_lshl_add_u64 v[192:193], v[190:191], 0, s[8:9]
	s_add_i32 m0, s58, 0x4000
	v_mfma_f32_16x16x32_bf16 v[94:97], v[174:177], v[114:117], v[94:97]
	v_lshl_add_u64 v[190:191], v[190:191], 0, s[34:35]
	v_mfma_f32_16x16x32_bf16 v[90:93], v[174:177], v[118:121], v[90:93]
	v_mfma_f32_16x16x32_bf16 v[86:89], v[174:177], v[126:129], v[86:89]
	v_mfma_f32_16x16x32_bf16 v[82:85], v[174:177], v[134:137], v[82:85]
	global_load_lds_dwordx4 v[192:193], off
	s_add_i32 m0, s58, 0x6000
	s_add_u32 s52, s57, s52
	s_addc_u32 s53, s56, s53
	v_mfma_f32_16x16x32_bf16 v[78:81], v[174:177], v[142:145], v[78:81]
	v_mfma_f32_16x16x32_bf16 v[74:77], v[174:177], v[146:149], v[74:77]
	v_mfma_f32_16x16x32_bf16 v[70:73], v[174:177], v[154:157], v[70:73]
	v_mfma_f32_16x16x32_bf16 v[66:69], v[174:177], v[138:141], v[66:69]
	global_load_lds_dwordx4 v[190:191], off
	v_lshl_add_u64 v[190:191], s[52:53], 0, v[0:1]
	s_add_i32 m0, s58, 0x8000
	v_lshl_add_u64 v[192:193], v[190:191], 0, s[14:15]
	v_mfma_f32_16x16x32_bf16 v[62:65], v[170:173], v[114:117], v[62:65]
	v_mfma_f32_16x16x32_bf16 v[58:61], v[170:173], v[118:121], v[58:61]
	v_mfma_f32_16x16x32_bf16 v[54:57], v[170:173], v[126:129], v[54:57]
	v_mfma_f32_16x16x32_bf16 v[50:53], v[170:173], v[134:137], v[50:53]
	global_load_lds_dwordx4 v[190:191], off
	s_add_i32 m0, s58, 0xa000
	v_mfma_f32_16x16x32_bf16 v[46:49], v[170:173], v[142:145], v[46:49]
	v_mfma_f32_16x16x32_bf16 v[42:45], v[170:173], v[146:149], v[42:45]
	v_mfma_f32_16x16x32_bf16 v[38:41], v[170:173], v[154:157], v[38:41]
	v_mfma_f32_16x16x32_bf16 v[34:37], v[170:173], v[138:141], v[34:37]
	global_load_lds_dwordx4 v[192:193], off
	v_lshl_add_u64 v[192:193], v[190:191], 0, s[8:9]
	s_add_i32 m0, s58, 0xc000
	v_lshl_add_u64 v[190:191], v[190:191], 0, s[34:35]
	v_mfma_f32_16x16x32_bf16 v[30:33], v[166:169], v[114:117], v[30:33]
	v_mfma_f32_16x16x32_bf16 v[26:29], v[166:169], v[118:121], v[26:29]
	v_mfma_f32_16x16x32_bf16 v[22:25], v[166:169], v[126:129], v[22:25]
	v_mfma_f32_16x16x32_bf16 v[18:21], v[166:169], v[134:137], v[18:21]
	global_load_lds_dwordx4 v[192:193], off
	s_add_i32 m0, s58, 0xe000
	v_mfma_f32_16x16x32_bf16 v[14:17], v[166:169], v[142:145], v[14:17]
	s_cmp_eq_u32 s23, 16
	v_mfma_f32_16x16x32_bf16 v[10:13], v[166:169], v[146:149], v[10:13]
	v_mfma_f32_16x16x32_bf16 v[6:9], v[166:169], v[154:157], v[6:9]
	v_add_u32_e32 v154, s36, v185
	v_add3_u32 v174, v154, v189, v188
	v_add3_u32 v146, v154, v187, v188
	v_mfma_f32_16x16x32_bf16 v[2:5], v[166:169], v[138:141], v[2:5]
	global_load_lds_dwordx4 v[190:191], off
	ds_read_b128 v[154:157], v174 offset:32768
	ds_read_b128 v[166:169], v174 offset:34816
	ds_read_b128 v[170:173], v174 offset:36864
	ds_read_b128 v[174:177], v174 offset:38912
	ds_read_b128 v[114:117], v146
	ds_read_b128 v[118:121], v146 offset:2048
	ds_read_b128 v[122:125], v146 offset:4096
	ds_read_b128 v[126:129], v146 offset:6144
	ds_read_b128 v[134:137], v146 offset:8192
	ds_read_b128 v[138:141], v146 offset:10240
	ds_read_b128 v[142:145], v146 offset:12288
	ds_read_b128 v[146:149], v146 offset:14336
	s_waitcnt lgkmcnt(0)
; DEVI void gemm16s(f32x4 (&acc)[4][8], const GUnit& cur, const GUnit& nxt, bool has_next, bool first, int& stg, bfu* lds) {
;     ...
; #pragma unroll 1
;     for (int kt = 0; kt < nkt; ++kt) {
;       G16_HEAD()
;       ISSUE16(Ai, Bi, sAi, sBi, vAi, vBi, tk, st ^ 1);
;       G16_MM(ctf, cwf)
;       bf16x8 tf0[8], wf0[4];
;       G16_RD(tf0, wf0, 0)
;       G16_MM(tf0, wf0)
;       bf16x8 tf1[8], wf1[4];
;       G16_RD(tf1, wf1, 1)
; #pragma unroll
;       for (int mi = 0; mi < 8; ++mi) ctf[mi] = tf1[mi];
; #pragma unroll
;       for (int ni = 0; ni < 4; ++ni) cwf[ni] = wf1[ni];
; #pragma unroll
;       for (int i = 0; i < 8; ++i) {
;         __builtin_amdgcn_sched_group_barrier(0x008, 4, 0);
;         __builtin_amdgcn_sched_group_barrier(0x020, 1, 0);
;       }
;       __builtin_amdgcn_sched_group_barrier(0x100, 12, 0);
; #pragma unroll
;       for (int i = 0; i < 12; ++i) {
;         __builtin_amdgcn_sched_group_barrier(0x008, 2, 0);
;         __builtin_amdgcn_sched_group_barrier(0x100, 1, 0);
;       }
;       __builtin_amdgcn_sched_group_barrier(0x008, 8, 0);
;       st ^= 1;
;     }
;     G16_MM(ctf, cwf)
	v_mfma_f32_16x16x32_bf16 v[162:165], v[154:157], v[114:117], v[162:165]
	v_mfma_f32_16x16x32_bf16 v[158:161], v[154:157], v[118:121], v[158:161]
	v_mfma_f32_16x16x32_bf16 v[150:153], v[154:157], v[122:125], v[150:153]
	v_mfma_f32_16x16x32_bf16 v[130:133], v[154:157], v[126:129], v[130:133]
	v_mfma_f32_16x16x32_bf16 v[94:97], v[166:169], v[114:117], v[94:97]
	v_mfma_f32_16x16x32_bf16 v[90:93], v[166:169], v[118:121], v[90:93]
	v_mfma_f32_16x16x32_bf16 v[86:89], v[166:169], v[122:125], v[86:89]
	v_mfma_f32_16x16x32_bf16 v[82:85], v[166:169], v[126:129], v[82:85]
	v_mfma_f32_16x16x32_bf16 v[78:81], v[166:169], v[134:137], v[78:81]
	v_mfma_f32_16x16x32_bf16 v[74:77], v[166:169], v[138:141], v[74:77]
	v_mfma_f32_16x16x32_bf16 v[70:73], v[166:169], v[142:145], v[70:73]
	v_mfma_f32_16x16x32_bf16 v[66:69], v[166:169], v[146:149], v[66:69]
	v_mfma_f32_16x16x32_bf16 v[62:65], v[170:173], v[114:117], v[62:65]
	v_mfma_f32_16x16x32_bf16 v[58:61], v[170:173], v[118:121], v[58:61]
	v_mfma_f32_16x16x32_bf16 v[54:57], v[170:173], v[122:125], v[54:57]
	v_mfma_f32_16x16x32_bf16 v[50:53], v[170:173], v[126:129], v[50:53]
	v_mfma_f32_16x16x32_bf16 v[46:49], v[170:173], v[134:137], v[46:49]
	v_mfma_f32_16x16x32_bf16 v[42:45], v[170:173], v[138:141], v[42:45]
	v_mfma_f32_16x16x32_bf16 v[38:41], v[170:173], v[142:145], v[38:41]
	v_mfma_f32_16x16x32_bf16 v[34:37], v[170:173], v[146:149], v[34:37]
	v_mfma_f32_16x16x32_bf16 v[22:25], v[174:177], v[122:125], v[22:25]
	v_add_u32_e32 v122, s36, v186
	v_add3_u32 v123, v122, v187, v188
	v_add3_u32 v166, v122, v189, v188
	ds_read_b128 v[170:173], v166 offset:36864
	v_mfma_f32_16x16x32_bf16 v[110:113], v[154:157], v[134:137], v[110:113]
	v_mfma_f32_16x16x32_bf16 v[106:109], v[154:157], v[138:141], v[106:109]
	v_mfma_f32_16x16x32_bf16 v[30:33], v[174:177], v[114:117], v[30:33]
	v_mfma_f32_16x16x32_bf16 v[26:29], v[174:177], v[118:121], v[26:29]
	v_mfma_f32_16x16x32_bf16 v[18:21], v[174:177], v[126:129], v[18:21]
	v_mfma_f32_16x16x32_bf16 v[14:17], v[174:177], v[134:137], v[14:17]
	v_mfma_f32_16x16x32_bf16 v[10:13], v[174:177], v[138:141], v[10:13]
	v_mfma_f32_16x16x32_bf16 v[6:9], v[174:177], v[142:145], v[6:9]
	v_mfma_f32_16x16x32_bf16 v[2:5], v[174:177], v[146:149], v[2:5]
	ds_read_b128 v[174:177], v166 offset:34816
	v_mfma_f32_16x16x32_bf16 v[102:105], v[154:157], v[142:145], v[102:105]
	v_mfma_f32_16x16x32_bf16 v[98:101], v[154:157], v[146:149], v[98:101]
	ds_read_b128 v[138:141], v123 offset:14336
	ds_read_b128 v[154:157], v123 offset:12288
	ds_read_b128 v[146:149], v123 offset:10240
	ds_read_b128 v[142:145], v123 offset:8192
	ds_read_b128 v[134:137], v123 offset:6144
	ds_read_b128 v[126:129], v123 offset:4096
	ds_read_b128 v[118:121], v123 offset:2048
	ds_read_b128 v[114:117], v123
	ds_read_b128 v[122:125], v166 offset:32768
	ds_read_b128 v[166:169], v166 offset:38912
	s_cbranch_scc0 .LBB0_214
	s_waitcnt lgkmcnt(0)
	v_mfma_f32_16x16x32_bf16 v[162:165], v[122:125], v[114:117], v[162:165]
	v_mfma_f32_16x16x32_bf16 v[158:161], v[122:125], v[118:121], v[158:161]
	v_mfma_f32_16x16x32_bf16 v[150:153], v[122:125], v[126:129], v[150:153]
	v_mfma_f32_16x16x32_bf16 v[130:133], v[122:125], v[134:137], v[130:133]
	v_mfma_f32_16x16x32_bf16 v[110:113], v[122:125], v[142:145], v[110:113]
	v_mfma_f32_16x16x32_bf16 v[106:109], v[122:125], v[146:149], v[106:109]
	v_mfma_f32_16x16x32_bf16 v[102:105], v[122:125], v[154:157], v[102:105]
	v_mfma_f32_16x16x32_bf16 v[98:101], v[122:125], v[138:141], v[98:101]
	v_mfma_f32_16x16x32_bf16 v[94:97], v[174:177], v[114:117], v[94:97]
	v_mfma_f32_16x16x32_bf16 v[90:93], v[174:177], v[118:121], v[90:93]
	v_mfma_f32_16x16x32_bf16 v[86:89], v[174:177], v[126:129], v[86:89]
	v_mfma_f32_16x16x32_bf16 v[82:85], v[174:177], v[134:137], v[82:85]
	v_mfma_f32_16x16x32_bf16 v[78:81], v[174:177], v[142:145], v[78:81]
	v_mfma_f32_16x16x32_bf16 v[74:77], v[174:177], v[146:149], v[74:77]
	v_mfma_f32_16x16x32_bf16 v[70:73], v[174:177], v[154:157], v[70:73]
	v_mfma_f32_16x16x32_bf16 v[66:69], v[174:177], v[138:141], v[66:69]
	v_mfma_f32_16x16x32_bf16 v[62:65], v[170:173], v[114:117], v[62:65]
	v_mfma_f32_16x16x32_bf16 v[58:61], v[170:173], v[118:121], v[58:61]
	v_mfma_f32_16x16x32_bf16 v[54:57], v[170:173], v[126:129], v[54:57]
	v_mfma_f32_16x16x32_bf16 v[50:53], v[170:173], v[134:137], v[50:53]
	v_mfma_f32_16x16x32_bf16 v[46:49], v[170:173], v[142:145], v[46:49]
	v_mfma_f32_16x16x32_bf16 v[42:45], v[170:173], v[146:149], v[42:45]
	v_mfma_f32_16x16x32_bf16 v[38:41], v[170:173], v[154:157], v[38:41]
	v_mfma_f32_16x16x32_bf16 v[34:37], v[170:173], v[138:141], v[34:37]
	v_mfma_f32_16x16x32_bf16 v[30:33], v[166:169], v[114:117], v[30:33]
	v_mfma_f32_16x16x32_bf16 v[26:29], v[166:169], v[118:121], v[26:29]
	v_mfma_f32_16x16x32_bf16 v[22:25], v[166:169], v[126:129], v[22:25]
	v_mfma_f32_16x16x32_bf16 v[18:21], v[166:169], v[134:137], v[18:21]
	v_mfma_f32_16x16x32_bf16 v[14:17], v[166:169], v[142:145], v[14:17]
	v_mfma_f32_16x16x32_bf16 v[10:13], v[166:169], v[146:149], v[10:13]
	v_mfma_f32_16x16x32_bf16 v[6:9], v[166:169], v[154:157], v[6:9]
	v_mfma_f32_16x16x32_bf16 v[2:5], v[166:169], v[138:141], v[2:5]

; DEVI void gemm16s(f32x4 (&acc)[4][8], const GUnit& cur, const GUnit& nxt, bool has_next, bool first, int& stg, bfu* lds) {
;     ...
; #pragma unroll 1
;     for (int kt = 0; kt < nkt; ++kt) {
;       G16_HEAD()
;       ISSUE16(Ai, Bi, sAi, sBi, vAi, vBi, tk, st ^ 1);
;       G16_MM(ctf, cwf)
;       bf16x8 tf0[8], wf0[4];
;       G16_RD(tf0, wf0, 0)
;       G16_MM(tf0, wf0)
;       bf16x8 tf1[8], wf1[4];
;       G16_RD(tf1, wf1, 1)
; #pragma unroll
;       for (int mi = 0; mi < 8; ++mi) ctf[mi] = tf1[mi];
; #pragma unroll
;       for (int ni = 0; ni < 4; ++ni) cwf[ni] = wf1[ni];
; #pragma unroll
;       for (int i = 0; i < 8; ++i) {
;         __builtin_amdgcn_sched_group_barrier(0x008, 4, 0);
;         __builtin_amdgcn_sched_group_barrier(0x020, 1, 0);
;       }
;       __builtin_amdgcn_sched_group_barrier(0x100, 12, 0);
; #pragma unroll
;       for (int i = 0; i < 12; ++i) {
;         __builtin_amdgcn_sched_group_barrier(0x008, 2, 0);
;         __builtin_amdgcn_sched_group_barrier(0x100, 1, 0);
;       }
;       __builtin_amdgcn_sched_group_barrier(0x008, 8, 0);
;       st ^= 1;
;     }
.LBB0_236:
	s_setprio 1
	s_add_i32 s23, s30, 1
	s_cmp_gt_u32 s30, 14
	s_cselect_b64 s[36:37], -1, 0
	s_and_b64 s[58:59], s[36:37], exec
	s_cselect_b32 s30, s57, s23
	s_and_b64 s[36:37], s[40:41], s[36:37]
	s_and_b64 s[36:37], s[36:37], exec
	s_cselect_b32 s37, s43, s47
	s_cselect_b32 s60, s29, s46
	s_cselect_b32 s62, s56, s49
	s_cselect_b32 s63, s55, s48
	s_lshl_b32 s36, s20, 16
	s_xor_b32 s20, s20, 1
	s_lshl_b32 s58, s20, 16
	s_addk_i32 s36, 0xc20
	s_add_i32 s64, s28, s58
	s_lshl_b64 s[58:59], s[30:31], 7
	s_add_u32 s60, s60, s58
	s_addc_u32 s61, s37, s59
	s_waitcnt vmcnt(0)
	v_lshl_add_u64 v[190:191], s[60:61], 0, v[0:1]
	s_mov_b32 m0, s64
	s_waitcnt lgkmcnt(0)
	s_barrier
	v_lshl_add_u64 v[192:193], v[190:191], 0, s[14:15]
	s_waitcnt lgkmcnt(0)
	v_mfma_f32_16x16x32_bf16 v[162:165], v[134:137], v[126:129], v[162:165]
	s_mov_b32 s30, s23
	v_mfma_f32_16x16x32_bf16 v[114:117], v[134:137], v[130:133], v[114:117]
	v_mfma_f32_16x16x32_bf16 v[98:101], v[134:137], v[138:141], v[98:101]
	v_mfma_f32_16x16x32_bf16 v[82:85], v[134:137], v[142:145], v[82:85]
	global_load_lds_dwordx4 v[190:191], off
	s_add_i32 m0, s64, 0x2000
	v_mfma_f32_16x16x32_bf16 v[66:69], v[134:137], v[150:153], v[66:69]
	v_mfma_f32_16x16x32_bf16 v[50:53], v[134:137], v[154:157], v[50:53]
	v_mfma_f32_16x16x32_bf16 v[34:37], v[134:137], v[158:161], v[34:37]
	v_mfma_f32_16x16x32_bf16 v[18:21], v[134:137], v[146:149], v[18:21]
	global_load_lds_dwordx4 v[192:193], off
	v_lshl_add_u64 v[192:193], v[190:191], 0, s[8:9]
	s_add_i32 m0, s64, 0x4000
	v_mfma_f32_16x16x32_bf16 v[122:125], v[174:177], v[126:129], v[122:125]
	v_lshl_add_u64 v[190:191], v[190:191], 0, s[34:35]
	v_mfma_f32_16x16x32_bf16 v[106:109], v[174:177], v[130:133], v[106:109]
	v_mfma_f32_16x16x32_bf16 v[90:93], v[174:177], v[138:141], v[90:93]
	v_mfma_f32_16x16x32_bf16 v[74:77], v[174:177], v[142:145], v[74:77]
	global_load_lds_dwordx4 v[192:193], off
	s_add_i32 m0, s64, 0x6000
	s_add_u32 s58, s63, s58
	s_addc_u32 s59, s62, s59
	v_mfma_f32_16x16x32_bf16 v[58:61], v[174:177], v[150:153], v[58:61]
	v_mfma_f32_16x16x32_bf16 v[42:45], v[174:177], v[154:157], v[42:45]
	v_mfma_f32_16x16x32_bf16 v[26:29], v[174:177], v[158:161], v[26:29]
	v_mfma_f32_16x16x32_bf16 v[10:13], v[174:177], v[146:149], v[10:13]
	global_load_lds_dwordx4 v[190:191], off
	v_lshl_add_u64 v[190:191], s[58:59], 0, v[0:1]
	s_add_i32 m0, s64, 0x8000
	v_lshl_add_u64 v[192:193], v[190:191], 0, s[14:15]
	v_mfma_f32_16x16x32_bf16 v[118:121], v[170:173], v[126:129], v[118:121]
	v_mfma_f32_16x16x32_bf16 v[102:105], v[170:173], v[130:133], v[102:105]
	v_mfma_f32_16x16x32_bf16 v[86:89], v[170:173], v[138:141], v[86:89]
	v_mfma_f32_16x16x32_bf16 v[70:73], v[170:173], v[142:145], v[70:73]
	global_load_lds_dwordx4 v[190:191], off
	s_add_i32 m0, s64, 0xa000
	v_mfma_f32_16x16x32_bf16 v[54:57], v[170:173], v[150:153], v[54:57]
	v_mfma_f32_16x16x32_bf16 v[38:41], v[170:173], v[154:157], v[38:41]
	v_mfma_f32_16x16x32_bf16 v[22:25], v[170:173], v[158:161], v[22:25]
	v_mfma_f32_16x16x32_bf16 v[6:9], v[170:173], v[146:149], v[6:9]
	global_load_lds_dwordx4 v[192:193], off
	v_lshl_add_u64 v[192:193], v[190:191], 0, s[8:9]
	s_add_i32 m0, s64, 0xc000
	v_lshl_add_u64 v[190:191], v[190:191], 0, s[34:35]
	v_mfma_f32_16x16x32_bf16 v[110:113], v[166:169], v[126:129], v[110:113]
	v_mfma_f32_16x16x32_bf16 v[94:97], v[166:169], v[130:133], v[94:97]
	v_mfma_f32_16x16x32_bf16 v[78:81], v[166:169], v[138:141], v[78:81]
	v_mfma_f32_16x16x32_bf16 v[62:65], v[166:169], v[142:145], v[62:65]
	global_load_lds_dwordx4 v[192:193], off
	s_add_i32 m0, s64, 0xe000
	v_mfma_f32_16x16x32_bf16 v[46:49], v[166:169], v[150:153], v[46:49]
	s_cmp_eq_u32 s23, 16
	v_mfma_f32_16x16x32_bf16 v[30:33], v[166:169], v[154:157], v[30:33]
	v_mfma_f32_16x16x32_bf16 v[14:17], v[166:169], v[158:161], v[14:17]
	v_add_u32_e32 v158, s36, v184
	v_add3_u32 v174, v158, v188, v187
	v_add3_u32 v154, v158, v186, v187
	v_mfma_f32_16x16x32_bf16 v[2:5], v[166:169], v[146:149], v[2:5]
	global_load_lds_dwordx4 v[190:191], off
	ds_read_b128 v[158:161], v174 offset:32768
	ds_read_b128 v[166:169], v174 offset:34816
	ds_read_b128 v[170:173], v174 offset:36864
	ds_read_b128 v[174:177], v174 offset:38912
	ds_read_b128 v[126:129], v154
	ds_read_b128 v[130:133], v154 offset:2048
	ds_read_b128 v[134:137], v154 offset:4096
	ds_read_b128 v[138:141], v154 offset:6144
	ds_read_b128 v[142:145], v154 offset:8192
	ds_read_b128 v[146:149], v154 offset:10240
	ds_read_b128 v[150:153], v154 offset:12288
	ds_read_b128 v[154:157], v154 offset:14336
	s_waitcnt lgkmcnt(0)
; DEVI void gemm16s(f32x4 (&acc)[4][8], const GUnit& cur, const GUnit& nxt, bool has_next, bool first, int& stg, bfu* lds) {
;     ...
; #pragma unroll 1
;     for (int kt = 0; kt < nkt; ++kt) {
;       G16_HEAD()
;       ISSUE16(Ai, Bi, sAi, sBi, vAi, vBi, tk, st ^ 1);
;       G16_MM(ctf, cwf)
;       bf16x8 tf0[8], wf0[4];
;       G16_RD(tf0, wf0, 0)
;       G16_MM(tf0, wf0)
;       bf16x8 tf1[8], wf1[4];
;       G16_RD(tf1, wf1, 1)
; #pragma unroll
;       for (int mi = 0; mi < 8; ++mi) ctf[mi] = tf1[mi];
; #pragma unroll
;       for (int ni = 0; ni < 4; ++ni) cwf[ni] = wf1[ni];
; #pragma unroll
;       for (int i = 0; i < 8; ++i) {
;         __builtin_amdgcn_sched_group_barrier(0x008, 4, 0);
;         __builtin_amdgcn_sched_group_barrier(0x020, 1, 0);
;       }
;       __builtin_amdgcn_sched_group_barrier(0x100, 12, 0);
; #pragma unroll
;       for (int i = 0; i < 12; ++i) {
;         __builtin_amdgcn_sched_group_barrier(0x008, 2, 0);
;         __builtin_amdgcn_sched_group_barrier(0x100, 1, 0);
;       }
;       __builtin_amdgcn_sched_group_barrier(0x008, 8, 0);
;       st ^= 1;
;     }
;     G16_MM(ctf, cwf)
	v_mfma_f32_16x16x32_bf16 v[162:165], v[158:161], v[126:129], v[162:165]
	v_mfma_f32_16x16x32_bf16 v[114:117], v[158:161], v[130:133], v[114:117]
	v_mfma_f32_16x16x32_bf16 v[98:101], v[158:161], v[134:137], v[98:101]
	v_mfma_f32_16x16x32_bf16 v[82:85], v[158:161], v[138:141], v[82:85]
	v_mfma_f32_16x16x32_bf16 v[122:125], v[166:169], v[126:129], v[122:125]
	v_mfma_f32_16x16x32_bf16 v[106:109], v[166:169], v[130:133], v[106:109]
	v_mfma_f32_16x16x32_bf16 v[90:93], v[166:169], v[134:137], v[90:93]
	v_mfma_f32_16x16x32_bf16 v[74:77], v[166:169], v[138:141], v[74:77]
	v_mfma_f32_16x16x32_bf16 v[58:61], v[166:169], v[142:145], v[58:61]
	v_mfma_f32_16x16x32_bf16 v[42:45], v[166:169], v[146:149], v[42:45]
	v_mfma_f32_16x16x32_bf16 v[26:29], v[166:169], v[150:153], v[26:29]
	v_mfma_f32_16x16x32_bf16 v[10:13], v[166:169], v[154:157], v[10:13]
	v_mfma_f32_16x16x32_bf16 v[118:121], v[170:173], v[126:129], v[118:121]
	v_mfma_f32_16x16x32_bf16 v[102:105], v[170:173], v[130:133], v[102:105]
	v_mfma_f32_16x16x32_bf16 v[86:89], v[170:173], v[134:137], v[86:89]
	v_mfma_f32_16x16x32_bf16 v[70:73], v[170:173], v[138:141], v[70:73]
	v_mfma_f32_16x16x32_bf16 v[54:57], v[170:173], v[142:145], v[54:57]
	v_mfma_f32_16x16x32_bf16 v[38:41], v[170:173], v[146:149], v[38:41]
	v_mfma_f32_16x16x32_bf16 v[22:25], v[170:173], v[150:153], v[22:25]
	v_mfma_f32_16x16x32_bf16 v[6:9], v[170:173], v[154:157], v[6:9]
	v_mfma_f32_16x16x32_bf16 v[78:81], v[174:177], v[134:137], v[78:81]
	v_add_u32_e32 v134, s36, v185
	v_add3_u32 v135, v134, v186, v187
	v_add3_u32 v166, v134, v188, v187
	ds_read_b128 v[170:173], v166 offset:36864
	v_mfma_f32_16x16x32_bf16 v[66:69], v[158:161], v[142:145], v[66:69]
	v_mfma_f32_16x16x32_bf16 v[50:53], v[158:161], v[146:149], v[50:53]
	v_mfma_f32_16x16x32_bf16 v[110:113], v[174:177], v[126:129], v[110:113]
	v_mfma_f32_16x16x32_bf16 v[94:97], v[174:177], v[130:133], v[94:97]
	v_mfma_f32_16x16x32_bf16 v[62:65], v[174:177], v[138:141], v[62:65]
	v_mfma_f32_16x16x32_bf16 v[46:49], v[174:177], v[142:145], v[46:49]
	v_mfma_f32_16x16x32_bf16 v[30:33], v[174:177], v[146:149], v[30:33]
	v_mfma_f32_16x16x32_bf16 v[14:17], v[174:177], v[150:153], v[14:17]
	v_mfma_f32_16x16x32_bf16 v[2:5], v[174:177], v[154:157], v[2:5]
	ds_read_b128 v[174:177], v166 offset:34816
	v_mfma_f32_16x16x32_bf16 v[34:37], v[158:161], v[150:153], v[34:37]
	v_mfma_f32_16x16x32_bf16 v[18:21], v[158:161], v[154:157], v[18:21]
	ds_read_b128 v[146:149], v135 offset:14336
	ds_read_b128 v[158:161], v135 offset:12288
	ds_read_b128 v[154:157], v135 offset:10240
	ds_read_b128 v[150:153], v135 offset:8192
	ds_read_b128 v[142:145], v135 offset:6144
	ds_read_b128 v[138:141], v135 offset:4096
	ds_read_b128 v[130:133], v135 offset:2048
	ds_read_b128 v[126:129], v135
	ds_read_b128 v[134:137], v166 offset:32768
	ds_read_b128 v[166:169], v166 offset:38912
	s_cbranch_scc0 .LBB0_236
	s_waitcnt lgkmcnt(0)
	v_mfma_f32_16x16x32_bf16 v[162:165], v[134:137], v[126:129], v[162:165]
	v_mfma_f32_16x16x32_bf16 v[114:117], v[134:137], v[130:133], v[114:117]
	v_mfma_f32_16x16x32_bf16 v[98:101], v[134:137], v[138:141], v[98:101]
	v_mfma_f32_16x16x32_bf16 v[82:85], v[134:137], v[142:145], v[82:85]
	v_mfma_f32_16x16x32_bf16 v[66:69], v[134:137], v[150:153], v[66:69]
	v_mfma_f32_16x16x32_bf16 v[50:53], v[134:137], v[154:157], v[50:53]
	v_mfma_f32_16x16x32_bf16 v[34:37], v[134:137], v[158:161], v[34:37]
	v_mfma_f32_16x16x32_bf16 v[18:21], v[134:137], v[146:149], v[18:21]
	v_mfma_f32_16x16x32_bf16 v[122:125], v[174:177], v[126:129], v[122:125]
	v_mfma_f32_16x16x32_bf16 v[106:109], v[174:177], v[130:133], v[106:109]
	v_mfma_f32_16x16x32_bf16 v[90:93], v[174:177], v[138:141], v[90:93]
	v_mfma_f32_16x16x32_bf16 v[74:77], v[174:177], v[142:145], v[74:77]
	v_mfma_f32_16x16x32_bf16 v[58:61], v[174:177], v[150:153], v[58:61]
	v_mfma_f32_16x16x32_bf16 v[42:45], v[174:177], v[154:157], v[42:45]
	v_mfma_f32_16x16x32_bf16 v[26:29], v[174:177], v[158:161], v[26:29]
	v_mfma_f32_16x16x32_bf16 v[10:13], v[174:177], v[146:149], v[10:13]
	v_mfma_f32_16x16x32_bf16 v[118:121], v[170:173], v[126:129], v[118:121]
	v_mfma_f32_16x16x32_bf16 v[102:105], v[170:173], v[130:133], v[102:105]
	v_mfma_f32_16x16x32_bf16 v[86:89], v[170:173], v[138:141], v[86:89]
	v_mfma_f32_16x16x32_bf16 v[70:73], v[170:173], v[142:145], v[70:73]
	v_mfma_f32_16x16x32_bf16 v[54:57], v[170:173], v[150:153], v[54:57]
	v_mfma_f32_16x16x32_bf16 v[38:41], v[170:173], v[154:157], v[38:41]
	v_mfma_f32_16x16x32_bf16 v[22:25], v[170:173], v[158:161], v[22:25]
	v_mfma_f32_16x16x32_bf16 v[6:9], v[170:173], v[146:149], v[6:9]
	v_mfma_f32_16x16x32_bf16 v[110:113], v[166:169], v[126:129], v[110:113]
	v_mfma_f32_16x16x32_bf16 v[94:97], v[166:169], v[130:133], v[94:97]
	v_mfma_f32_16x16x32_bf16 v[78:81], v[166:169], v[138:141], v[78:81]
	v_mfma_f32_16x16x32_bf16 v[62:65], v[166:169], v[142:145], v[62:65]
	v_mfma_f32_16x16x32_bf16 v[46:49], v[166:169], v[150:153], v[46:49]
	v_mfma_f32_16x16x32_bf16 v[30:33], v[166:169], v[154:157], v[30:33]
	v_mfma_f32_16x16x32_bf16 v[14:17], v[166:169], v[158:161], v[14:17]
	v_mfma_f32_16x16x32_bf16 v[2:5], v[166:169], v[146:149], v[2:5]

; DEVI float lo2f(unsigned u) { return __uint_as_float(u << 16); }
; DEVI float hi2f(unsigned u) { return __uint_as_float(u & 0xffff0000u); }
; DEVI void phase_resid_gemm(const Params& p, const bfu* A, int lda, int nkt, const bfu* wT, int ldb, const float* resid32,
;                            float* ssq_out, float* out32, char* lds) {
;     ...
;         if (resid32) r = *(const float4*)(resid32 + (long)m * 1024 + n);
;         else { const uint2 u = *(const uint2*)(xs + (long)m * LDX + n); r = make_float4(lo2f(u.x), hi2f(u.x), lo2f(u.y), hi2f(u.y)); }
.LBB0_247:
	s_setprio 0
	s_mov_b64 s[36:37], -1

; DEVI void gemm16s(f32x4 (&acc)[4][8], const GUnit& cur, const GUnit& nxt, bool has_next, bool first, int& stg, bfu* lds) {
;     ...
; #pragma unroll 1
;     for (int kt = 0; kt < nkt; ++kt) {
;       G16_HEAD()
;       ISSUE16(Ai, Bi, sAi, sBi, vAi, vBi, tk, st ^ 1);
;       G16_MM(ctf, cwf)
;       bf16x8 tf0[8], wf0[4];
;       G16_RD(tf0, wf0, 0)
;       G16_MM(tf0, wf0)
;       bf16x8 tf1[8], wf1[4];
;       G16_RD(tf1, wf1, 1)
; #pragma unroll
;       for (int mi = 0; mi < 8; ++mi) ctf[mi] = tf1[mi];
; #pragma unroll
;       for (int ni = 0; ni < 4; ++ni) cwf[ni] = wf1[ni];
; #pragma unroll
;       for (int i = 0; i < 8; ++i) {
;         __builtin_amdgcn_sched_group_barrier(0x008, 4, 0);
;         __builtin_amdgcn_sched_group_barrier(0x020, 1, 0);
;       }
;       __builtin_amdgcn_sched_group_barrier(0x100, 12, 0);
; #pragma unroll
;       for (int i = 0; i < 12; ++i) {
;         __builtin_amdgcn_sched_group_barrier(0x008, 2, 0);
;         __builtin_amdgcn_sched_group_barrier(0x100, 1, 0);
;       }
;       __builtin_amdgcn_sched_group_barrier(0x008, 8, 0);
;       st ^= 1;
;     }
.LBB0_685:
	s_setprio 1
	s_add_i32 s23, s30, 1
	s_cmp_gt_u32 s30, 14
	s_cselect_b64 s[36:37], -1, 0
	s_and_b64 s[58:59], s[36:37], exec
	s_cselect_b32 s30, s56, s23
	s_and_b64 s[36:37], s[0:1], s[36:37]
	s_and_b64 s[36:37], s[36:37], exec
	s_cselect_b32 s37, s29, s41
	s_cselect_b32 s57, s28, s40
	s_cselect_b32 s62, s55, s45
	s_cselect_b32 s63, s54, s44
	s_lshl_b32 s36, s20, 16
	s_xor_b32 s20, s20, 1
	s_lshl_b32 s58, s20, 16
	s_addk_i32 s36, 0xc20
	s_add_i32 s64, s27, s58
	s_lshl_b64 s[58:59], s[30:31], 7
	s_add_u32 s60, s57, s58
	s_addc_u32 s61, s37, s59
	s_waitcnt vmcnt(0)
	v_lshl_add_u64 v[192:193], s[60:61], 0, v[184:185]
	s_mov_b32 m0, s64
	s_waitcnt lgkmcnt(0)
	s_barrier
	v_lshl_add_u64 v[194:195], v[192:193], 0, s[14:15]
	s_waitcnt lgkmcnt(0)
	v_mfma_f32_16x16x32_bf16 v[162:165], v[122:125], v[114:117], v[162:165]
	s_mov_b32 s30, s23
	v_mfma_f32_16x16x32_bf16 v[158:161], v[122:125], v[118:121], v[158:161]
	v_mfma_f32_16x16x32_bf16 v[150:153], v[122:125], v[126:129], v[150:153]
	v_mfma_f32_16x16x32_bf16 v[130:133], v[122:125], v[134:137], v[130:133]
	global_load_lds_dwordx4 v[192:193], off
	s_add_i32 m0, s64, 0x2000
	v_mfma_f32_16x16x32_bf16 v[110:113], v[122:125], v[142:145], v[110:113]
	v_mfma_f32_16x16x32_bf16 v[106:109], v[122:125], v[146:149], v[106:109]
	v_mfma_f32_16x16x32_bf16 v[82:85], v[122:125], v[154:157], v[82:85]
	v_mfma_f32_16x16x32_bf16 v[58:61], v[122:125], v[138:141], v[58:61]
	global_load_lds_dwordx4 v[194:195], off
	v_lshl_add_u64 v[194:195], v[192:193], 0, s[8:9]
	s_add_i32 m0, s64, 0x4000
	v_mfma_f32_16x16x32_bf16 v[102:105], v[174:177], v[114:117], v[102:105]
	v_lshl_add_u64 v[192:193], v[192:193], 0, s[34:35]
	v_mfma_f32_16x16x32_bf16 v[98:101], v[174:177], v[118:121], v[98:101]
	v_mfma_f32_16x16x32_bf16 v[94:97], v[174:177], v[126:129], v[94:97]
	v_mfma_f32_16x16x32_bf16 v[90:93], v[174:177], v[134:137], v[90:93]
	global_load_lds_dwordx4 v[194:195], off
	s_add_i32 m0, s64, 0x6000
	s_add_u32 s58, s63, s58
	s_addc_u32 s59, s62, s59
	v_mfma_f32_16x16x32_bf16 v[86:89], v[174:177], v[142:145], v[86:89]
	v_mfma_f32_16x16x32_bf16 v[78:81], v[174:177], v[146:149], v[78:81]
	v_mfma_f32_16x16x32_bf16 v[46:49], v[174:177], v[154:157], v[46:49]
	v_mfma_f32_16x16x32_bf16 v[14:17], v[174:177], v[138:141], v[14:17]
	global_load_lds_dwordx4 v[192:193], off
	v_lshl_add_u64 v[192:193], s[58:59], 0, v[184:185]
	s_add_i32 m0, s64, 0x8000
	v_lshl_add_u64 v[194:195], v[192:193], 0, s[14:15]
	v_mfma_f32_16x16x32_bf16 v[74:77], v[170:173], v[114:117], v[74:77]
	v_mfma_f32_16x16x32_bf16 v[70:73], v[170:173], v[118:121], v[70:73]
	v_mfma_f32_16x16x32_bf16 v[66:69], v[170:173], v[126:129], v[66:69]
	v_mfma_f32_16x16x32_bf16 v[62:65], v[170:173], v[134:137], v[62:65]
	global_load_lds_dwordx4 v[192:193], off
	s_add_i32 m0, s64, 0xa000
	v_mfma_f32_16x16x32_bf16 v[54:57], v[170:173], v[142:145], v[54:57]
	v_mfma_f32_16x16x32_bf16 v[50:53], v[170:173], v[146:149], v[50:53]
	v_mfma_f32_16x16x32_bf16 v[22:25], v[170:173], v[154:157], v[22:25]
	v_mfma_f32_16x16x32_bf16 v[6:9], v[170:173], v[138:141], v[6:9]
	global_load_lds_dwordx4 v[194:195], off
	v_lshl_add_u64 v[194:195], v[192:193], 0, s[8:9]
	s_add_i32 m0, s64, 0xc000
	v_lshl_add_u64 v[192:193], v[192:193], 0, s[34:35]
	v_mfma_f32_16x16x32_bf16 v[42:45], v[166:169], v[114:117], v[42:45]
	v_mfma_f32_16x16x32_bf16 v[38:41], v[166:169], v[118:121], v[38:41]
	v_mfma_f32_16x16x32_bf16 v[34:37], v[166:169], v[126:129], v[34:37]
	v_mfma_f32_16x16x32_bf16 v[30:33], v[166:169], v[134:137], v[30:33]
	global_load_lds_dwordx4 v[194:195], off
	s_add_i32 m0, s64, 0xe000
	v_mfma_f32_16x16x32_bf16 v[26:29], v[166:169], v[142:145], v[26:29]
	s_cmp_eq_u32 s23, 16
	v_mfma_f32_16x16x32_bf16 v[18:21], v[166:169], v[146:149], v[18:21]
	v_mfma_f32_16x16x32_bf16 v[10:13], v[166:169], v[154:157], v[10:13]
	v_add_u32_e32 v154, s36, v187
	v_add3_u32 v174, v154, v191, v190
	v_add3_u32 v146, v154, v189, v190
	v_mfma_f32_16x16x32_bf16 v[2:5], v[166:169], v[138:141], v[2:5]
	global_load_lds_dwordx4 v[192:193], off
	ds_read_b128 v[154:157], v174 offset:32768
	ds_read_b128 v[166:169], v174 offset:34816
	ds_read_b128 v[170:173], v174 offset:36864
	ds_read_b128 v[174:177], v174 offset:38912
	ds_read_b128 v[114:117], v146
	ds_read_b128 v[118:121], v146 offset:2048
	ds_read_b128 v[122:125], v146 offset:4096
	ds_read_b128 v[126:129], v146 offset:6144
	ds_read_b128 v[134:137], v146 offset:8192
	ds_read_b128 v[138:141], v146 offset:10240
	ds_read_b128 v[142:145], v146 offset:12288
	ds_read_b128 v[146:149], v146 offset:14336
	s_waitcnt lgkmcnt(0)
; DEVI void gemm16s(f32x4 (&acc)[4][8], const GUnit& cur, const GUnit& nxt, bool has_next, bool first, int& stg, bfu* lds) {
;     ...
; #pragma unroll 1
;     for (int kt = 0; kt < nkt; ++kt) {
;       G16_HEAD()
;       ISSUE16(Ai, Bi, sAi, sBi, vAi, vBi, tk, st ^ 1);
;       G16_MM(ctf, cwf)
;       bf16x8 tf0[8], wf0[4];
;       G16_RD(tf0, wf0, 0)
;       G16_MM(tf0, wf0)
;       bf16x8 tf1[8], wf1[4];
;       G16_RD(tf1, wf1, 1)
; #pragma unroll
;       for (int mi = 0; mi < 8; ++mi) ctf[mi] = tf1[mi];
; #pragma unroll
;       for (int ni = 0; ni < 4; ++ni) cwf[ni] = wf1[ni];
; #pragma unroll
;       for (int i = 0; i < 8; ++i) {
;         __builtin_amdgcn_sched_group_barrier(0x008, 4, 0);
;         __builtin_amdgcn_sched_group_barrier(0x020, 1, 0);
;       }
;       __builtin_amdgcn_sched_group_barrier(0x100, 12, 0);
; #pragma unroll
;       for (int i = 0; i < 12; ++i) {
;         __builtin_amdgcn_sched_group_barrier(0x008, 2, 0);
;         __builtin_amdgcn_sched_group_barrier(0x100, 1, 0);
;       }
;       __builtin_amdgcn_sched_group_barrier(0x008, 8, 0);
;       st ^= 1;
;     }
;     G16_MM(ctf, cwf)
	v_mfma_f32_16x16x32_bf16 v[162:165], v[154:157], v[114:117], v[162:165]
	v_mfma_f32_16x16x32_bf16 v[158:161], v[154:157], v[118:121], v[158:161]
	v_mfma_f32_16x16x32_bf16 v[150:153], v[154:157], v[122:125], v[150:153]
	v_mfma_f32_16x16x32_bf16 v[130:133], v[154:157], v[126:129], v[130:133]
	v_mfma_f32_16x16x32_bf16 v[102:105], v[166:169], v[114:117], v[102:105]
	v_mfma_f32_16x16x32_bf16 v[98:101], v[166:169], v[118:121], v[98:101]
	v_mfma_f32_16x16x32_bf16 v[94:97], v[166:169], v[122:125], v[94:97]
	v_mfma_f32_16x16x32_bf16 v[90:93], v[166:169], v[126:129], v[90:93]
	v_mfma_f32_16x16x32_bf16 v[86:89], v[166:169], v[134:137], v[86:89]
	v_mfma_f32_16x16x32_bf16 v[78:81], v[166:169], v[138:141], v[78:81]
	v_mfma_f32_16x16x32_bf16 v[46:49], v[166:169], v[142:145], v[46:49]
	v_mfma_f32_16x16x32_bf16 v[14:17], v[166:169], v[146:149], v[14:17]
	v_mfma_f32_16x16x32_bf16 v[74:77], v[170:173], v[114:117], v[74:77]
	v_mfma_f32_16x16x32_bf16 v[70:73], v[170:173], v[118:121], v[70:73]
	v_mfma_f32_16x16x32_bf16 v[66:69], v[170:173], v[122:125], v[66:69]
	v_mfma_f32_16x16x32_bf16 v[62:65], v[170:173], v[126:129], v[62:65]
	v_mfma_f32_16x16x32_bf16 v[54:57], v[170:173], v[134:137], v[54:57]
	v_mfma_f32_16x16x32_bf16 v[50:53], v[170:173], v[138:141], v[50:53]
	v_mfma_f32_16x16x32_bf16 v[22:25], v[170:173], v[142:145], v[22:25]
	v_mfma_f32_16x16x32_bf16 v[6:9], v[170:173], v[146:149], v[6:9]
	v_mfma_f32_16x16x32_bf16 v[34:37], v[174:177], v[122:125], v[34:37]
	v_add_u32_e32 v122, s36, v188
	v_add3_u32 v123, v122, v189, v190
	v_add3_u32 v166, v122, v191, v190
	ds_read_b128 v[170:173], v166 offset:36864
	v_mfma_f32_16x16x32_bf16 v[110:113], v[154:157], v[134:137], v[110:113]
	v_mfma_f32_16x16x32_bf16 v[106:109], v[154:157], v[138:141], v[106:109]
	v_mfma_f32_16x16x32_bf16 v[42:45], v[174:177], v[114:117], v[42:45]
	v_mfma_f32_16x16x32_bf16 v[38:41], v[174:177], v[118:121], v[38:41]
	v_mfma_f32_16x16x32_bf16 v[30:33], v[174:177], v[126:129], v[30:33]
	v_mfma_f32_16x16x32_bf16 v[26:29], v[174:177], v[134:137], v[26:29]
	v_mfma_f32_16x16x32_bf16 v[18:21], v[174:177], v[138:141], v[18:21]
	v_mfma_f32_16x16x32_bf16 v[10:13], v[174:177], v[142:145], v[10:13]
	v_mfma_f32_16x16x32_bf16 v[2:5], v[174:177], v[146:149], v[2:5]
	ds_read_b128 v[174:177], v166 offset:34816
	v_mfma_f32_16x16x32_bf16 v[82:85], v[154:157], v[142:145], v[82:85]
	v_mfma_f32_16x16x32_bf16 v[58:61], v[154:157], v[146:149], v[58:61]
	ds_read_b128 v[138:141], v123 offset:14336
	ds_read_b128 v[154:157], v123 offset:12288
	ds_read_b128 v[146:149], v123 offset:10240
	ds_read_b128 v[142:145], v123 offset:8192
	ds_read_b128 v[134:137], v123 offset:6144
	ds_read_b128 v[126:129], v123 offset:4096
	ds_read_b128 v[118:121], v123 offset:2048
	ds_read_b128 v[114:117], v123
	ds_read_b128 v[122:125], v166 offset:32768
	ds_read_b128 v[166:169], v166 offset:38912
	s_cbranch_scc0 .LBB0_685
	s_waitcnt lgkmcnt(0)
	v_mfma_f32_16x16x32_bf16 v[162:165], v[122:125], v[114:117], v[162:165]
	v_mfma_f32_16x16x32_bf16 v[158:161], v[122:125], v[118:121], v[158:161]
	v_mfma_f32_16x16x32_bf16 v[150:153], v[122:125], v[126:129], v[150:153]
	v_mfma_f32_16x16x32_bf16 v[130:133], v[122:125], v[134:137], v[130:133]
	v_mfma_f32_16x16x32_bf16 v[110:113], v[122:125], v[142:145], v[110:113]
	v_mfma_f32_16x16x32_bf16 v[106:109], v[122:125], v[146:149], v[106:109]
	v_mfma_f32_16x16x32_bf16 v[82:85], v[122:125], v[154:157], v[82:85]
	v_mfma_f32_16x16x32_bf16 v[58:61], v[122:125], v[138:141], v[58:61]
	v_mfma_f32_16x16x32_bf16 v[102:105], v[174:177], v[114:117], v[102:105]
	v_mfma_f32_16x16x32_bf16 v[98:101], v[174:177], v[118:121], v[98:101]
	v_mfma_f32_16x16x32_bf16 v[94:97], v[174:177], v[126:129], v[94:97]
	v_mfma_f32_16x16x32_bf16 v[90:93], v[174:177], v[134:137], v[90:93]
	v_mfma_f32_16x16x32_bf16 v[86:89], v[174:177], v[142:145], v[86:89]
	v_mfma_f32_16x16x32_bf16 v[78:81], v[174:177], v[146:149], v[78:81]
	v_mfma_f32_16x16x32_bf16 v[46:49], v[174:177], v[154:157], v[46:49]
	v_mfma_f32_16x16x32_bf16 v[14:17], v[174:177], v[138:141], v[14:17]
	v_mfma_f32_16x16x32_bf16 v[74:77], v[170:173], v[114:117], v[74:77]
	v_mfma_f32_16x16x32_bf16 v[70:73], v[170:173], v[118:121], v[70:73]
	v_mfma_f32_16x16x32_bf16 v[66:69], v[170:173], v[126:129], v[66:69]
	v_mfma_f32_16x16x32_bf16 v[62:65], v[170:173], v[134:137], v[62:65]
	v_mfma_f32_16x16x32_bf16 v[54:57], v[170:173], v[142:145], v[54:57]
	v_mfma_f32_16x16x32_bf16 v[50:53], v[170:173], v[146:149], v[50:53]
	v_mfma_f32_16x16x32_bf16 v[22:25], v[170:173], v[154:157], v[22:25]
	v_mfma_f32_16x16x32_bf16 v[6:9], v[170:173], v[138:141], v[6:9]
	v_mfma_f32_16x16x32_bf16 v[42:45], v[166:169], v[114:117], v[42:45]
	v_mfma_f32_16x16x32_bf16 v[38:41], v[166:169], v[118:121], v[38:41]
	v_mfma_f32_16x16x32_bf16 v[34:37], v[166:169], v[126:129], v[34:37]
	v_mfma_f32_16x16x32_bf16 v[30:33], v[166:169], v[134:137], v[30:33]
	v_mfma_f32_16x16x32_bf16 v[26:29], v[166:169], v[142:145], v[26:29]
	v_mfma_f32_16x16x32_bf16 v[18:21], v[166:169], v[146:149], v[18:21]
	v_mfma_f32_16x16x32_bf16 v[10:13], v[166:169], v[154:157], v[10:13]
	v_mfma_f32_16x16x32_bf16 v[2:5], v[166:169], v[138:141], v[2:5]

; DEVI void phase2(const Params& p, int l, char* lds) {
;     ...
; #pragma unroll
;     for (int mi = 0; mi < 8; ++mi) {
;       const float rs = rsS[wm * 128 + mi * 16 + fr];
; #pragma unroll
;       for (int ni = 0; ni < 4; ++ni) acc[ni][mi] *= rs;
;     }
;     const bool do_gelu = (n0 < 512);
;     const int kind = (nt_cur == 2) ? 1 : ((nt_cur == 4 && wn < 2) ? 2 : ((nt_cur == 5 && wn < 2) ? 3 : 0));
;     if (kind) {
;       const float* gain = (kind == 1) ? (p.in[7] + l * 64) : (p.in[8] + (l * 3 + (kind == 2 ? 1 : 2)) * 64);
.LBB0_689:
	s_setprio 0
	v_bfe_u32 v254, v225, 4, 1
	v_mov_b32_e32 v255, 0
	v_mul_u32_u24_e32 v254, 24, v254
	v_lshlrev_b32_e32 v114, 2, v179
	v_add3_u32 v138, s25, v181, v114
	ds_read2_b32 v[116:117], v138 offset1:16
	s_cmp_lg_u32 s52, 2
	s_cselect_b64 vcc, -1, 0
	s_cmp_eq_u32 s52, 4
	s_cselect_b64 s[0:1], -1, 0
	s_waitcnt lgkmcnt(0)
	v_pk_mul_f32 v[134:135], v[164:165], v[116:117] op_sel_hi:[1,0]
	v_pk_mul_f32 v[136:137], v[162:163], v[116:117] op_sel_hi:[1,0]
	v_pk_mul_f32 v[104:105], v[104:105], v[116:117] op_sel_hi:[1,0]
	v_pk_mul_f32 v[114:115], v[102:103], v[116:117] op_sel_hi:[1,0]
	v_pk_mul_f32 v[76:77], v[76:77], v[116:117] op_sel_hi:[1,0]
	v_pk_mul_f32 v[74:75], v[74:75], v[116:117] op_sel_hi:[1,0]
	v_pk_mul_f32 v[44:45], v[44:45], v[116:117] op_sel_hi:[1,0]
	v_pk_mul_f32 v[42:43], v[42:43], v[116:117] op_sel_hi:[1,0]
	v_mov_b32_e32 v102, v117
	ds_read2_b32 v[116:117], v138 offset0:32 offset1:48
	v_pk_mul_f32 v[126:127], v[160:161], v[102:103] op_sel_hi:[1,0]
	v_pk_mul_f32 v[128:129], v[158:159], v[102:103] op_sel_hi:[1,0]
	v_pk_mul_f32 v[100:101], v[100:101], v[102:103] op_sel_hi:[1,0]
	v_pk_mul_f32 v[98:99], v[98:99], v[102:103] op_sel_hi:[1,0]
	v_pk_mul_f32 v[72:73], v[72:73], v[102:103] op_sel_hi:[1,0]
	v_pk_mul_f32 v[70:71], v[70:71], v[102:103] op_sel_hi:[1,0]
	v_pk_mul_f32 v[40:41], v[40:41], v[102:103] op_sel_hi:[1,0]
	v_pk_mul_f32 v[38:39], v[38:39], v[102:103] op_sel_hi:[1,0]
	s_waitcnt lgkmcnt(0)
	v_pk_mul_f32 v[102:103], v[94:95], v[116:117] op_sel_hi:[1,0]
	v_mov_b32_e32 v94, v117
	v_pk_mul_f32 v[120:121], v[130:131], v[94:95] op_sel_hi:[1,0]
	ds_read2_b32 v[130:131], v138 offset0:64 offset1:80
	v_pk_mul_f32 v[122:123], v[152:153], v[116:117] op_sel_hi:[1,0]
	v_pk_mul_f32 v[124:125], v[150:151], v[116:117] op_sel_hi:[1,0]
	v_pk_mul_f32 v[96:97], v[96:97], v[116:117] op_sel_hi:[1,0]
	v_pk_mul_f32 v[68:69], v[68:69], v[116:117] op_sel_hi:[1,0]
	v_pk_mul_f32 v[66:67], v[66:67], v[116:117] op_sel_hi:[1,0]
	v_pk_mul_f32 v[36:37], v[36:37], v[116:117] op_sel_hi:[1,0]
	v_pk_mul_f32 v[34:35], v[34:35], v[116:117] op_sel_hi:[1,0]
	v_pk_mul_f32 v[118:119], v[132:133], v[94:95] op_sel_hi:[1,0]
	v_pk_mul_f32 v[92:93], v[92:93], v[94:95] op_sel_hi:[1,0]
	v_pk_mul_f32 v[90:91], v[90:91], v[94:95] op_sel_hi:[1,0]
	v_pk_mul_f32 v[64:65], v[64:65], v[94:95] op_sel_hi:[1,0]
	v_pk_mul_f32 v[62:63], v[62:63], v[94:95] op_sel_hi:[1,0]
	v_pk_mul_f32 v[32:33], v[32:33], v[94:95] op_sel_hi:[1,0]
	v_pk_mul_f32 v[30:31], v[30:31], v[94:95] op_sel_hi:[1,0]
	s_waitcnt lgkmcnt(0)
	v_pk_mul_f32 v[112:113], v[112:113], v[130:131] op_sel_hi:[1,0]
	v_pk_mul_f32 v[116:117], v[110:111], v[130:131] op_sel_hi:[1,0]
	v_pk_mul_f32 v[88:89], v[88:89], v[130:131] op_sel_hi:[1,0]
	v_pk_mul_f32 v[94:95], v[86:87], v[130:131] op_sel_hi:[1,0]
	v_pk_mul_f32 v[56:57], v[56:57], v[130:131] op_sel_hi:[1,0]
	v_pk_mul_f32 v[54:55], v[54:55], v[130:131] op_sel_hi:[1,0]
	v_pk_mul_f32 v[28:29], v[28:29], v[130:131] op_sel_hi:[1,0]
	v_pk_mul_f32 v[26:27], v[26:27], v[130:131] op_sel_hi:[1,0]
	v_mov_b32_e32 v130, v131
	v_pk_mul_f32 v[108:109], v[108:109], v[130:131] op_sel_hi:[1,0]
	v_pk_mul_f32 v[110:111], v[106:107], v[130:131] op_sel_hi:[1,0]
	v_pk_mul_f32 v[80:81], v[80:81], v[130:131] op_sel_hi:[1,0]
	v_pk_mul_f32 v[86:87], v[78:79], v[130:131] op_sel_hi:[1,0]
	v_pk_mul_f32 v[52:53], v[52:53], v[130:131] op_sel_hi:[1,0]
	v_pk_mul_f32 v[50:51], v[50:51], v[130:131] op_sel_hi:[1,0]
	v_pk_mul_f32 v[20:21], v[20:21], v[130:131] op_sel_hi:[1,0]
	v_pk_mul_f32 v[18:19], v[18:19], v[130:131] op_sel_hi:[1,0]
	ds_read2_b32 v[130:131], v138 offset0:96 offset1:112
	s_and_b64 s[36:37], s[0:1], s[38:39]
	s_cmp_eq_u32 s52, 5
	s_cselect_b64 s[0:1], -1, 0
	s_and_b64 s[0:1], s[0:1], s[38:39]
	s_waitcnt lgkmcnt(0)
	v_pk_mul_f32 v[84:85], v[84:85], v[130:131] op_sel_hi:[1,0]
	v_pk_mul_f32 v[106:107], v[82:83], v[130:131] op_sel_hi:[1,0]
	v_pk_mul_f32 v[78:79], v[48:49], v[130:131] op_sel_hi:[1,0]
	v_pk_mul_f32 v[82:83], v[46:47], v[130:131] op_sel_hi:[1,0]
	v_pk_mul_f32 v[24:25], v[24:25], v[130:131] op_sel_hi:[1,0]
	v_pk_mul_f32 v[22:23], v[22:23], v[130:131] op_sel_hi:[1,0]
	v_pk_mul_f32 v[12:13], v[12:13], v[130:131] op_sel_hi:[1,0]
	v_pk_mul_f32 v[10:11], v[10:11], v[130:131] op_sel_hi:[1,0]
	v_mov_b32_e32 v130, v131
	v_pk_mul_f32 v[48:49], v[14:15], v[130:131] op_sel_hi:[1,0]
	v_pk_mul_f32 v[14:15], v[8:9], v[130:131] op_sel_hi:[1,0]
	v_pk_mul_f32 v[8:9], v[2:3], v[130:131] op_sel_hi:[1,0]
	v_cndmask_b32_e64 v2, 0, 3, s[0:1]
	v_cndmask_b32_e64 v2, v2, 2, s[36:37]
	v_cndmask_b32_e32 v2, 1, v2, vcc
	v_pk_mul_f32 v[60:61], v[60:61], v[130:131] op_sel_hi:[1,0]
	v_pk_mul_f32 v[58:59], v[58:59], v[130:131] op_sel_hi:[1,0]
	v_pk_mul_f32 v[46:47], v[16:17], v[130:131] op_sel_hi:[1,0]
	v_pk_mul_f32 v[16:17], v[6:7], v[130:131] op_sel_hi:[1,0]
	v_pk_mul_f32 v[6:7], v[4:5], v[130:131] op_sel_hi:[1,0]
	v_cmp_lt_i32_e64 s[0:1], 0, v2
	s_and_saveexec_b64 s[40:41], s[0:1]
	s_cbranch_execz .LBB0_693
	v_cmp_ne_u32_e64 s[0:1], 1, v2
	v_mov_b32_e32 v131, 0x3e38aa3b
	v_mov_b64_e32 v[2:3], s[4:5]
	s_and_saveexec_b64 s[44:45], s[0:1]
	s_cbranch_execz .LBB0_692
	s_and_b64 s[0:1], vcc, s[36:37]
	v_cndmask_b32_e64 v2, 2, 1, s[0:1]
	v_readlane_b32 s0, v242, 43
	s_mul_i32 s0, s0, 3
	v_readlane_b32 s56, v244, 19
	v_add_lshl_u32 v2, v2, s0, 6
	v_ashrrev_i32_e32 v3, 31, v2
	v_readlane_b32 s57, v244, 20
	v_mov_b32_e32 v131, 1.0
	v_readlane_b32 s1, v242, 44
	v_lshl_add_u64 v[2:3], v[2:3], 2, s[56:57]
	v_readlane_b32 s58, v244, 21
	v_readlane_b32 s59, v244, 22
	v_readlane_b32 s60, v244, 23
	v_readlane_b32 s61, v244, 24
	v_readlane_b32 s62, v244, 25
	v_readlane_b32 s63, v244, 26
	v_readlane_b32 s64, v244, 27
	v_readlane_b32 s65, v244, 28
	v_readlane_b32 s66, v244, 29
	v_readlane_b32 s67, v244, 30
	v_readlane_b32 s68, v244, 31
	v_readlane_b32 s69, v244, 32
	v_readlane_b32 s70, v244, 33
	v_readlane_b32 s71, v244, 34
